# GEMM K-loops (in-proj, out-proj): LDS-DMA addresses as SGPR base + 32-bit VGPR offset, sixteen 64-bit VALU adds per iteration removed
# baseline (speedup 1.0000x reference)
; #define PG8_STAGE(bufoff, gbase, voff) do { _Pragma("unroll") for (int _i = 0; _i < 2; ++_i) \
;         __builtin_amdgcn_global_load_lds((const unsigned*)((const char*)(gbase) + (voff)[_i]), (PG8_LAS unsigned*)(lds + (bufoff) + ldsw + _i * 8192), 16, 0, 0); } while (0)
; #define PG8_LDA(dst, b, h) do { _Pragma("unroll") for (int m = 0; m < 4; ++m) _Pragma("unroll") for (int k = 0; k < 2; ++k) dst[m][k] = *(const PG8_LAS bf16x8*)(lds + PG8_SA(b, h) + aoff + m * 2048 + k * 1024); } while (0)
; #define PG8_LDB(dst, b, h) do { _Pragma("unroll") for (int n = 0; n < 2; ++n) _Pragma("unroll") for (int k = 0; k < 2; ++k) dst[n][k] = *(const PG8_LAS bf16x8*)(lds + PG8_SB(b, h) + boff + n * 2048 + k * 1024); } while (0)
; #define PG8_MMA(ai, bj, At, Bt) do { __builtin_amdgcn_s_setprio(1); _Pragma("unroll") for (int m = 0; m < 4; ++m) _Pragma("unroll") for (int n = 0; n < 2; ++n) _Pragma("unroll") for (int k = 0; k < 2; ++k) \
;         acc[ai][bj][m][n] = mma16<Epi::I8>(Bt[n][k], At[m][k], acc[ai][bj][m][n]); __builtin_amdgcn_s_setprio(0); } while (0)
; #define PG8_WAIT_V(n) asm volatile("s_waitcnt vmcnt(" #n ")" ::: "memory")
; #define PG8_WAIT_L(n) asm volatile("s_waitcnt lgkmcnt(" #n ")" ::: "memory")
; #define PG8_BAR __builtin_amdgcn_s_barrier()
; #define PG8_SCHED __builtin_amdgcn_sched_barrier(0)
; template <class Epi, class Sched, bool ALIGN_EPI = false, bool SP2 = false>
; __device__ __forceinline__ void gemm_phase(PG8_LAS unsigned char* lds, const Gemm g, const Sched& S, const Epi& E, int wid  ) {
;     ...
;             if constexpr (SP2) {
;             PG8_LDB(B0, 0, 0); PG8_LDB(B1, 0, 1); PG8_SCHED; PG8_LDA(At, 0, 0); PG8_STAGE(PG8_SA(1, 1), a1 + hstep, voffA);
;             PG8_WAIT_V(8); PG8_WAIT_L(0); PG8_BAR; PG8_MMA(0, 0, At, B0); PG8_MMA(0, 1, At, B1); PG8_BAR; PG8_SCHED;
;             PG8_LDA(At, 0, 1); PG8_STAGE(PG8_SB(0, 0), b2, voffB); PG8_STAGE(PG8_SB(0, 1), b2 + hstep, voffB); PG8_STAGE(PG8_SA(0, 0), a2, voffA);
;             PG8_WAIT_V(8); PG8_WAIT_L(0); PG8_BAR; PG8_MMA(1, 0, At, B0); PG8_MMA(1, 1, At, B1); PG8_BAR; PG8_SCHED;
.LBB0_155:
	ds_read_b128 v[108:111], v168
	ds_read_b128 v[112:115], v168 offset:1024
	ds_read_b128 v[120:123], v168 offset:2048
	ds_read_b128 v[128:131], v168 offset:3072
	ds_read_b128 v[172:175], v169
	ds_read_b128 v[176:179], v169 offset:1024
	ds_read_b128 v[180:183], v169 offset:2048
	ds_read_b128 v[184:187], v169 offset:3072
	s_add_u32 s22, s20, 0xfffc0080
	s_addc_u32 s23, s21, -1
	s_cmp_eq_u32 s42, 12
	s_cselect_b32 s25, s13, s23
	s_cselect_b32 s24, s38, s22
	s_cselect_b32 s23, s3, s41
	s_cselect_b32 s22, s39, s40
	s_add_i32 m0, s19, 0xc000
	ds_read_b128 v[188:191], v170
	ds_read_b128 v[192:195], v170 offset:1024
	ds_read_b128 v[196:199], v170 offset:2048
	ds_read_b128 v[200:203], v170 offset:3072
	ds_read_b128 v[204:207], v170 offset:4096
	ds_read_b128 v[208:211], v170 offset:5120
	ds_read_b128 v[212:215], v170 offset:6144
	ds_read_b128 v[216:219], v170 offset:7168
	global_load_lds_dwordx4 v154, s[20:21]
	s_add_i32 m0, s19, 0xe000
	s_nop 0
	global_load_lds_dwordx4 v156, s[20:21]
	s_waitcnt vmcnt(8)
	s_waitcnt lgkmcnt(0)
	s_barrier
	s_setprio 1
	s_waitcnt lgkmcnt(0)
	v_mfma_i32_16x16x64_i8 v[140:143], v[108:111], v[188:191], v[140:143]
	v_mfma_i32_16x16x64_i8 v[136:139], v[120:123], v[188:191], v[136:139]
	v_mfma_i32_16x16x64_i8 v[116:119], v[108:111], v[196:199], v[116:119]
	v_mfma_i32_16x16x64_i8 v[104:107], v[120:123], v[196:199], v[104:107]
	v_mfma_i32_16x16x64_i8 v[92:95], v[108:111], v[204:207], v[92:95]
	v_mfma_i32_16x16x64_i8 v[88:91], v[120:123], v[204:207], v[88:91]
	v_mfma_i32_16x16x64_i8 v[76:79], v[108:111], v[212:215], v[76:79]
	v_mfma_i32_16x16x64_i8 v[72:75], v[120:123], v[212:215], v[72:75]
	v_mfma_i32_16x16x64_i8 v[140:143], v[112:115], v[192:195], v[140:143]
	v_mfma_i32_16x16x64_i8 v[136:139], v[128:131], v[192:195], v[136:139]
	v_mfma_i32_16x16x64_i8 v[116:119], v[112:115], v[200:203], v[116:119]
	v_mfma_i32_16x16x64_i8 v[104:107], v[128:131], v[200:203], v[104:107]
	v_mfma_i32_16x16x64_i8 v[92:95], v[112:115], v[208:211], v[92:95]
	v_mfma_i32_16x16x64_i8 v[88:91], v[128:131], v[208:211], v[88:91]
	v_mfma_i32_16x16x64_i8 v[76:79], v[112:115], v[216:219], v[76:79]
	v_mfma_i32_16x16x64_i8 v[72:75], v[128:131], v[216:219], v[72:75]
	s_setprio 0
	s_setprio 1
	v_mfma_i32_16x16x64_i8 v[132:135], v[172:175], v[188:191], v[132:135]
	v_mfma_i32_16x16x64_i8 v[124:127], v[180:183], v[188:191], v[124:127]
	v_mfma_i32_16x16x64_i8 v[100:103], v[172:175], v[196:199], v[100:103]
	v_mfma_i32_16x16x64_i8 v[96:99], v[180:183], v[196:199], v[96:99]
	v_mfma_i32_16x16x64_i8 v[84:87], v[172:175], v[204:207], v[84:87]
	v_mfma_i32_16x16x64_i8 v[80:83], v[180:183], v[204:207], v[80:83]
	v_mfma_i32_16x16x64_i8 v[68:71], v[172:175], v[212:215], v[68:71]
	v_mfma_i32_16x16x64_i8 v[64:67], v[180:183], v[212:215], v[64:67]
	v_mfma_i32_16x16x64_i8 v[132:135], v[176:179], v[192:195], v[132:135]
	v_mfma_i32_16x16x64_i8 v[124:127], v[184:187], v[192:195], v[124:127]
	v_mfma_i32_16x16x64_i8 v[100:103], v[176:179], v[200:203], v[100:103]
	v_mfma_i32_16x16x64_i8 v[96:99], v[184:187], v[200:203], v[96:99]
	v_mfma_i32_16x16x64_i8 v[84:87], v[176:179], v[208:211], v[84:87]
	v_mfma_i32_16x16x64_i8 v[80:83], v[184:187], v[208:211], v[80:83]
	v_mfma_i32_16x16x64_i8 v[68:71], v[176:179], v[216:219], v[68:71]
	v_mfma_i32_16x16x64_i8 v[64:67], v[184:187], v[216:219], v[64:67]
	s_setprio 0
	s_barrier
	s_add_i32 s43, s35, s81
	s_add_u32 s98, s22, s0
	s_addc_u32 s99, s23, s1
	s_mov_b32 m0, s43
	ds_read_b128 v[188:191], v170 offset:16384
	ds_read_b128 v[192:195], v170 offset:17408
	ds_read_b128 v[196:199], v170 offset:18432
	ds_read_b128 v[200:203], v170 offset:19456
	ds_read_b128 v[204:207], v170 offset:20480
	ds_read_b128 v[208:211], v170 offset:21504
	ds_read_b128 v[212:215], v170 offset:22528
	ds_read_b128 v[216:219], v170 offset:23552
	global_load_lds_dwordx4 v148, s[22:23]
	s_add_i32 m0, s43, 0x2000
	s_add_u32 s44, s22, 0x40000
	s_addc_u32 s45, s23, 0
	s_add_i32 s43, s36, s81
	global_load_lds_dwordx4 v144, s[22:23]
	s_mov_b32 m0, s43
	s_add_u32 s100, s24, s0
	s_addc_u32 s101, s25, s1
	global_load_lds_dwordx4 v148, s[44:45]
	s_add_i32 m0, s43, 0x2000
	s_nop 0
	global_load_lds_dwordx4 v144, s[44:45]
	s_mov_b32 m0, s19
	s_nop 0
	global_load_lds_dwordx4 v150, s[24:25]
	s_mov_b32 m0, s27
	s_nop 0
	global_load_lds_dwordx4 v146, s[24:25]
	s_waitcnt vmcnt(8)
	s_waitcnt lgkmcnt(0)
	s_barrier
	s_setprio 1
	s_waitcnt lgkmcnt(0)
	v_mfma_i32_16x16x64_i8 v[60:63], v[108:111], v[188:191], v[60:63]
	v_mfma_i32_16x16x64_i8 v[56:59], v[120:123], v[188:191], v[56:59]
	v_mfma_i32_16x16x64_i8 v[44:47], v[108:111], v[196:199], v[44:47]
	v_mfma_i32_16x16x64_i8 v[40:43], v[120:123], v[196:199], v[40:43]
	v_mfma_i32_16x16x64_i8 v[28:31], v[108:111], v[204:207], v[28:31]
	v_mfma_i32_16x16x64_i8 v[24:27], v[120:123], v[204:207], v[24:27]
	v_mfma_i32_16x16x64_i8 v[12:15], v[108:111], v[212:215], v[12:15]
	v_mfma_i32_16x16x64_i8 v[8:11], v[120:123], v[212:215], v[8:11]
	v_mfma_i32_16x16x64_i8 v[60:63], v[112:115], v[192:195], v[60:63]
	v_mfma_i32_16x16x64_i8 v[56:59], v[128:131], v[192:195], v[56:59]
	v_mfma_i32_16x16x64_i8 v[44:47], v[112:115], v[200:203], v[44:47]
	v_mfma_i32_16x16x64_i8 v[40:43], v[128:131], v[200:203], v[40:43]
	v_mfma_i32_16x16x64_i8 v[28:31], v[112:115], v[208:211], v[28:31]
	v_mfma_i32_16x16x64_i8 v[24:27], v[128:131], v[208:211], v[24:27]
	v_mfma_i32_16x16x64_i8 v[12:15], v[112:115], v[216:219], v[12:15]
	v_mfma_i32_16x16x64_i8 v[8:11], v[128:131], v[216:219], v[8:11]
	s_setprio 0
	s_setprio 1
	v_mfma_i32_16x16x64_i8 v[52:55], v[172:175], v[188:191], v[52:55]
	v_mfma_i32_16x16x64_i8 v[48:51], v[180:183], v[188:191], v[48:51]
	v_mfma_i32_16x16x64_i8 v[36:39], v[172:175], v[196:199], v[36:39]
	v_mfma_i32_16x16x64_i8 v[32:35], v[180:183], v[196:199], v[32:35]
	v_mfma_i32_16x16x64_i8 v[20:23], v[172:175], v[204:207], v[20:23]
	v_mfma_i32_16x16x64_i8 v[16:19], v[180:183], v[204:207], v[16:19]
	v_mfma_i32_16x16x64_i8 v[4:7], v[172:175], v[212:215], v[4:7]
	v_mfma_i32_16x16x64_i8 v[0:3], v[180:183], v[212:215], v[0:3]
	v_mfma_i32_16x16x64_i8 v[52:55], v[176:179], v[192:195], v[52:55]
	v_mfma_i32_16x16x64_i8 v[48:51], v[184:187], v[192:195], v[48:51]
	v_mfma_i32_16x16x64_i8 v[36:39], v[176:179], v[200:203], v[36:39]
	v_mfma_i32_16x16x64_i8 v[32:35], v[184:187], v[200:203], v[32:35]
	v_mfma_i32_16x16x64_i8 v[20:23], v[176:179], v[208:211], v[20:23]
	v_mfma_i32_16x16x64_i8 v[16:19], v[184:187], v[208:211], v[16:19]
	v_mfma_i32_16x16x64_i8 v[4:7], v[176:179], v[216:219], v[4:7]
	v_mfma_i32_16x16x64_i8 v[0:3], v[184:187], v[216:219], v[0:3]
	s_setprio 0
	s_barrier
; #define PG8_STAGE(bufoff, gbase, voff) do { _Pragma("unroll") for (int _i = 0; _i < 2; ++_i) \
;         __builtin_amdgcn_global_load_lds((const unsigned*)((const char*)(gbase) + (voff)[_i]), (PG8_LAS unsigned*)(lds + (bufoff) + ldsw + _i * 8192), 16, 0, 0); } while (0)
; #define PG8_LDA(dst, b, h) do { _Pragma("unroll") for (int m = 0; m < 4; ++m) _Pragma("unroll") for (int k = 0; k < 2; ++k) dst[m][k] = *(const PG8_LAS bf16x8*)(lds + PG8_SA(b, h) + aoff + m * 2048 + k * 1024); } while (0)
; #define PG8_LDB(dst, b, h) do { _Pragma("unroll") for (int n = 0; n < 2; ++n) _Pragma("unroll") for (int k = 0; k < 2; ++k) dst[n][k] = *(const PG8_LAS bf16x8*)(lds + PG8_SB(b, h) + boff + n * 2048 + k * 1024); } while (0)
; #define PG8_MMA(ai, bj, At, Bt) do { __builtin_amdgcn_s_setprio(1); _Pragma("unroll") for (int m = 0; m < 4; ++m) _Pragma("unroll") for (int n = 0; n < 2; ++n) _Pragma("unroll") for (int k = 0; k < 2; ++k) \
;         acc[ai][bj][m][n] = mma16<Epi::I8>(Bt[n][k], At[m][k], acc[ai][bj][m][n]); __builtin_amdgcn_s_setprio(0); } while (0)
; #define PG8_WAIT_V(n) asm volatile("s_waitcnt vmcnt(" #n ")" ::: "memory")
; #define PG8_WAIT_L(n) asm volatile("s_waitcnt lgkmcnt(" #n ")" ::: "memory")
; #define PG8_BAR __builtin_amdgcn_s_barrier()
; #define PG8_SCHED __builtin_amdgcn_sched_barrier(0)
; template <class Epi, class Sched, bool ALIGN_EPI = false, bool SP2 = false>
; __device__ __forceinline__ void gemm_phase(PG8_LAS unsigned char* lds, const Gemm g, const Sched& S, const Epi& E, int wid  ) {
;     ...
;             PG8_LDB(B0, 1, 0); PG8_LDB(B1, 1, 1); PG8_SCHED; PG8_LDA(At, 1, 0); PG8_STAGE(PG8_SA(0, 1), a2 + hstep, voffA);
;             PG8_WAIT_V(8); PG8_WAIT_L(0); PG8_BAR; PG8_MMA(0, 0, At, B0); PG8_MMA(0, 1, At, B1); PG8_BAR; PG8_SCHED;
;             PG8_LDA(At, 1, 1); PG8_STAGE(PG8_SB(1, 0), b3, voffB); PG8_STAGE(PG8_SB(1, 1), b3 + hstep, voffB); PG8_STAGE(PG8_SA(1, 0), a3, voffA);
;             PG8_WAIT_V(8); PG8_WAIT_L(0); PG8_BAR; PG8_MMA(1, 0, At, B0); PG8_MMA(1, 1, At, B1); PG8_BAR; PG8_SCHED;
	s_add_i32 s43, 0, 0x18000
	s_add_i32 s44, 0, 0x1c000
	v_add_u32_e32 v128, s43, v166
	v_add_u32_e32 v171, s44, v166
	ds_read_b128 v[108:111], v128
	ds_read_b128 v[112:115], v128 offset:1024
	ds_read_b128 v[120:123], v128 offset:2048
	ds_read_b128 v[128:131], v128 offset:3072
	ds_read_b128 v[172:175], v171
	ds_read_b128 v[176:179], v171 offset:1024
	ds_read_b128 v[180:183], v171 offset:2048
	ds_read_b128 v[184:187], v171 offset:3072
	s_add_u32 s24, s24, 0x40000
	s_addc_u32 s25, s25, 0
	s_mov_b32 m0, s28
	ds_read_b128 v[188:191], v170 offset:32768
	ds_read_b128 v[192:195], v170 offset:33792
	ds_read_b128 v[196:199], v170 offset:34816
	ds_read_b128 v[200:203], v170 offset:35840
	ds_read_b128 v[204:207], v170 offset:36864
	ds_read_b128 v[208:211], v170 offset:37888
	ds_read_b128 v[212:215], v170 offset:38912
	ds_read_b128 v[216:219], v170 offset:39936
	global_load_lds_dwordx4 v150, s[24:25]
	s_mov_b32 m0, s29
	s_nop 0
	global_load_lds_dwordx4 v146, s[24:25]
	s_waitcnt vmcnt(8)
	s_waitcnt lgkmcnt(0)
	s_barrier
	s_setprio 1
	s_waitcnt lgkmcnt(0)
	v_mfma_i32_16x16x64_i8 v[140:143], v[108:111], v[188:191], v[140:143]
	v_mfma_i32_16x16x64_i8 v[136:139], v[120:123], v[188:191], v[136:139]
	v_mfma_i32_16x16x64_i8 v[116:119], v[108:111], v[196:199], v[116:119]
	v_mfma_i32_16x16x64_i8 v[104:107], v[120:123], v[196:199], v[104:107]
	v_mfma_i32_16x16x64_i8 v[92:95], v[108:111], v[204:207], v[92:95]
	v_mfma_i32_16x16x64_i8 v[88:91], v[120:123], v[204:207], v[88:91]
	v_mfma_i32_16x16x64_i8 v[76:79], v[108:111], v[212:215], v[76:79]
	v_mfma_i32_16x16x64_i8 v[72:75], v[120:123], v[212:215], v[72:75]
	v_mfma_i32_16x16x64_i8 v[140:143], v[112:115], v[192:195], v[140:143]
	v_mfma_i32_16x16x64_i8 v[136:139], v[128:131], v[192:195], v[136:139]
	v_mfma_i32_16x16x64_i8 v[116:119], v[112:115], v[200:203], v[116:119]
	v_mfma_i32_16x16x64_i8 v[104:107], v[128:131], v[200:203], v[104:107]
	v_mfma_i32_16x16x64_i8 v[92:95], v[112:115], v[208:211], v[92:95]
	v_mfma_i32_16x16x64_i8 v[88:91], v[128:131], v[208:211], v[88:91]
	v_mfma_i32_16x16x64_i8 v[76:79], v[112:115], v[216:219], v[76:79]
	v_mfma_i32_16x16x64_i8 v[72:75], v[128:131], v[216:219], v[72:75]
	s_setprio 0
	s_setprio 1
	v_mfma_i32_16x16x64_i8 v[132:135], v[172:175], v[188:191], v[132:135]
	v_mfma_i32_16x16x64_i8 v[124:127], v[180:183], v[188:191], v[124:127]
	v_mfma_i32_16x16x64_i8 v[100:103], v[172:175], v[196:199], v[100:103]
	v_mfma_i32_16x16x64_i8 v[96:99], v[180:183], v[196:199], v[96:99]
	v_mfma_i32_16x16x64_i8 v[84:87], v[172:175], v[204:207], v[84:87]
	v_mfma_i32_16x16x64_i8 v[80:83], v[180:183], v[204:207], v[80:83]
	v_mfma_i32_16x16x64_i8 v[68:71], v[172:175], v[212:215], v[68:71]
	v_mfma_i32_16x16x64_i8 v[64:67], v[180:183], v[212:215], v[64:67]
	v_mfma_i32_16x16x64_i8 v[132:135], v[176:179], v[192:195], v[132:135]
	v_mfma_i32_16x16x64_i8 v[124:127], v[184:187], v[192:195], v[124:127]
	v_mfma_i32_16x16x64_i8 v[100:103], v[176:179], v[200:203], v[100:103]
	v_mfma_i32_16x16x64_i8 v[96:99], v[184:187], v[200:203], v[96:99]
	v_mfma_i32_16x16x64_i8 v[84:87], v[176:179], v[208:211], v[84:87]
	v_mfma_i32_16x16x64_i8 v[80:83], v[184:187], v[208:211], v[80:83]
	v_mfma_i32_16x16x64_i8 v[68:71], v[176:179], v[216:219], v[68:71]
	v_mfma_i32_16x16x64_i8 v[64:67], v[184:187], v[216:219], v[64:67]
	s_setprio 0
	s_barrier
	s_add_i32 s24, s43, s81
	s_mov_b32 m0, s24
	ds_read_b128 v[188:191], v170 offset:49152
	ds_read_b128 v[192:195], v170 offset:50176
	ds_read_b128 v[196:199], v170 offset:51200
	ds_read_b128 v[200:203], v170 offset:52224
	ds_read_b128 v[204:207], v170 offset:53248
	ds_read_b128 v[208:211], v170 offset:54272
	ds_read_b128 v[212:215], v170 offset:55296
	ds_read_b128 v[216:219], v170 offset:56320
	global_load_lds_dwordx4 v148, s[98:99]
	s_add_i32 m0, s24, 0x2000
	s_add_u32 s22, s22, 0x40080
	s_addc_u32 s23, s23, 0
	s_add_i32 s24, s44, s81
	global_load_lds_dwordx4 v144, s[98:99]
	s_mov_b32 m0, s24
	s_nop 0
	global_load_lds_dwordx4 v148, s[22:23]
	s_add_i32 m0, s24, 0x2000
	s_nop 0
	global_load_lds_dwordx4 v144, s[22:23]
	s_mov_b32 m0, s33
	s_nop 0
	global_load_lds_dwordx4 v150, s[100:101]
	s_mov_b32 m0, s34
	s_nop 0
	global_load_lds_dwordx4 v146, s[100:101]
	s_waitcnt vmcnt(8)
	s_waitcnt lgkmcnt(0)
	s_barrier
	s_setprio 1
	s_waitcnt lgkmcnt(0)
	v_mfma_i32_16x16x64_i8 v[60:63], v[108:111], v[188:191], v[60:63]
	v_mfma_i32_16x16x64_i8 v[56:59], v[120:123], v[188:191], v[56:59]
	v_mfma_i32_16x16x64_i8 v[44:47], v[108:111], v[196:199], v[44:47]
	v_mfma_i32_16x16x64_i8 v[40:43], v[120:123], v[196:199], v[40:43]
	v_mfma_i32_16x16x64_i8 v[28:31], v[108:111], v[204:207], v[28:31]
	v_mfma_i32_16x16x64_i8 v[24:27], v[120:123], v[204:207], v[24:27]
	v_mfma_i32_16x16x64_i8 v[12:15], v[108:111], v[212:215], v[12:15]
	v_mfma_i32_16x16x64_i8 v[8:11], v[120:123], v[212:215], v[8:11]
	v_mfma_i32_16x16x64_i8 v[60:63], v[112:115], v[192:195], v[60:63]
	v_mfma_i32_16x16x64_i8 v[56:59], v[128:131], v[192:195], v[56:59]
	v_mfma_i32_16x16x64_i8 v[44:47], v[112:115], v[200:203], v[44:47]
	v_mfma_i32_16x16x64_i8 v[40:43], v[128:131], v[200:203], v[40:43]
	v_mfma_i32_16x16x64_i8 v[28:31], v[112:115], v[208:211], v[28:31]
	v_mfma_i32_16x16x64_i8 v[24:27], v[128:131], v[208:211], v[24:27]
	v_mfma_i32_16x16x64_i8 v[12:15], v[112:115], v[216:219], v[12:15]
	v_mfma_i32_16x16x64_i8 v[8:11], v[128:131], v[216:219], v[8:11]
	s_setprio 0
	s_setprio 1
	v_mfma_i32_16x16x64_i8 v[52:55], v[172:175], v[188:191], v[52:55]
	v_mfma_i32_16x16x64_i8 v[48:51], v[180:183], v[188:191], v[48:51]
	v_mfma_i32_16x16x64_i8 v[36:39], v[172:175], v[196:199], v[36:39]
	v_mfma_i32_16x16x64_i8 v[32:35], v[180:183], v[196:199], v[32:35]
	v_mfma_i32_16x16x64_i8 v[20:23], v[172:175], v[204:207], v[20:23]
	v_mfma_i32_16x16x64_i8 v[16:19], v[180:183], v[204:207], v[16:19]
	v_mfma_i32_16x16x64_i8 v[4:7], v[172:175], v[212:215], v[4:7]
	v_mfma_i32_16x16x64_i8 v[0:3], v[180:183], v[212:215], v[0:3]
	v_mfma_i32_16x16x64_i8 v[52:55], v[176:179], v[192:195], v[52:55]
	v_mfma_i32_16x16x64_i8 v[48:51], v[184:187], v[192:195], v[48:51]
	v_mfma_i32_16x16x64_i8 v[36:39], v[176:179], v[200:203], v[36:39]
	v_mfma_i32_16x16x64_i8 v[32:35], v[184:187], v[200:203], v[32:35]
	v_mfma_i32_16x16x64_i8 v[20:23], v[176:179], v[208:211], v[20:23]
	v_mfma_i32_16x16x64_i8 v[16:19], v[184:187], v[208:211], v[16:19]
	v_mfma_i32_16x16x64_i8 v[4:7], v[176:179], v[216:219], v[4:7]
	v_mfma_i32_16x16x64_i8 v[0:3], v[184:187], v[216:219], v[0:3]
	s_setprio 0
	s_barrier
	s_add_i32 s42, s42, 2
	s_add_u32 s20, s20, 0x100
	s_addc_u32 s21, s21, 0
	s_add_u32 s40, s40, 0x100
	s_addc_u32 s41, s41, 0
	s_cmp_gt_u32 s42, 13
	s_cbranch_scc0 .LBB0_155
	s_and_b64 vcc, exec, s[50:51]
	s_cbranch_vccz .LBB0_158
	s_barrier

; #define PG8_STAGE(bufoff, gbase, voff) do { _Pragma("unroll") for (int _i = 0; _i < 2; ++_i) \
;         __builtin_amdgcn_global_load_lds((const unsigned*)((const char*)(gbase) + (voff)[_i]), (PG8_LAS unsigned*)(lds + (bufoff) + ldsw + _i * 8192), 16, 0, 0); } while (0)
; #define PG8_LDA(dst, b, h) do { _Pragma("unroll") for (int m = 0; m < 4; ++m) _Pragma("unroll") for (int k = 0; k < 2; ++k) dst[m][k] = *(const PG8_LAS bf16x8*)(lds + PG8_SA(b, h) + aoff + m * 2048 + k * 1024); } while (0)
; #define PG8_LDB(dst, b, h) do { _Pragma("unroll") for (int n = 0; n < 2; ++n) _Pragma("unroll") for (int k = 0; k < 2; ++k) dst[n][k] = *(const PG8_LAS bf16x8*)(lds + PG8_SB(b, h) + boff + n * 2048 + k * 1024); } while (0)
; #define PG8_MMA(ai, bj, At, Bt) do { __builtin_amdgcn_s_setprio(1); _Pragma("unroll") for (int m = 0; m < 4; ++m) _Pragma("unroll") for (int n = 0; n < 2; ++n) _Pragma("unroll") for (int k = 0; k < 2; ++k) \
;         acc[ai][bj][m][n] = mma16<Epi::I8>(Bt[n][k], At[m][k], acc[ai][bj][m][n]); __builtin_amdgcn_s_setprio(0); } while (0)
; #define PG8_WAIT_V(n) asm volatile("s_waitcnt vmcnt(" #n ")" ::: "memory")
; #define PG8_WAIT_L(n) asm volatile("s_waitcnt lgkmcnt(" #n ")" ::: "memory")
; #define PG8_BAR __builtin_amdgcn_s_barrier()
; #define PG8_SCHED __builtin_amdgcn_sched_barrier(0)
; template <class Epi, class Sched, bool ALIGN_EPI = false, bool SP2 = false>
; __device__ __forceinline__ void gemm_phase(PG8_LAS unsigned char* lds, const Gemm g, const Sched& S, const Epi& E, int wid  ) {
;     ...
;             if constexpr (SP2) {
;             PG8_LDB(B0, 0, 0); PG8_LDB(B1, 0, 1); PG8_SCHED; PG8_LDA(At, 0, 0); PG8_STAGE(PG8_SA(1, 1), a1 + hstep, voffA);
;             PG8_WAIT_V(8); PG8_WAIT_L(0); PG8_BAR; PG8_MMA(0, 0, At, B0); PG8_MMA(0, 1, At, B1); PG8_BAR; PG8_SCHED;
;             PG8_LDA(At, 0, 1); PG8_STAGE(PG8_SB(0, 0), b2, voffB); PG8_STAGE(PG8_SB(0, 1), b2 + hstep, voffB); PG8_STAGE(PG8_SA(0, 0), a2, voffA);
;             PG8_WAIT_V(8); PG8_WAIT_L(0); PG8_BAR; PG8_MMA(1, 0, At, B0); PG8_MMA(1, 1, At, B1); PG8_BAR; PG8_SCHED;
.LBB0_510:
	ds_read_b128 v[128:131], v195
	ds_read_b128 v[132:135], v195 offset:1024
	ds_read_b128 v[136:139], v195 offset:2048
	ds_read_b128 v[140:143], v195 offset:3072
	ds_read_b128 v[144:147], v196
	ds_read_b128 v[148:151], v196 offset:1024
	ds_read_b128 v[152:155], v196 offset:2048
	ds_read_b128 v[156:159], v196 offset:3072
	s_add_u32 s28, s26, 0xfff80080
	s_addc_u32 s29, s27, -1
	s_cmp_eq_u32 s55, 28
	s_cselect_b32 s31, s3, s29
	s_cselect_b32 s30, s21, s28
	s_cselect_b32 s29, s19, s54
	s_cselect_b32 s28, s52, s53
	s_add_i32 m0, s39, 0xc000
	ds_read_b128 v[176:179], v197
	ds_read_b128 v[180:183], v197 offset:1024
	ds_read_b128 v[184:187], v197 offset:2048
	ds_read_b128 v[188:191], v197 offset:3072
	ds_read_b128 v[200:203], v197 offset:4096
	ds_read_b128 v[204:207], v197 offset:5120
	ds_read_b128 v[208:211], v197 offset:6144
	ds_read_b128 v[212:215], v197 offset:7168
	global_load_lds_dwordx4 v168, s[26:27]
	s_add_i32 m0, s39, 0xe000
	s_nop 0
	global_load_lds_dwordx4 v170, s[26:27]
	s_waitcnt vmcnt(8)
	s_waitcnt lgkmcnt(0)
	s_barrier
	s_setprio 1
	s_waitcnt lgkmcnt(0)
	v_mfma_f32_16x16x32_bf16 v[124:127], v[128:131], v[176:179], v[124:127]
	v_mfma_f32_16x16x32_bf16 v[120:123], v[136:139], v[176:179], v[120:123]
	v_mfma_f32_16x16x32_bf16 v[108:111], v[128:131], v[184:187], v[108:111]
	v_mfma_f32_16x16x32_bf16 v[104:107], v[136:139], v[184:187], v[104:107]
	v_mfma_f32_16x16x32_bf16 v[92:95], v[128:131], v[200:203], v[92:95]
	v_mfma_f32_16x16x32_bf16 v[88:91], v[136:139], v[200:203], v[88:91]
	v_mfma_f32_16x16x32_bf16 v[76:79], v[128:131], v[208:211], v[76:79]
	v_mfma_f32_16x16x32_bf16 v[72:75], v[136:139], v[208:211], v[72:75]
	v_mfma_f32_16x16x32_bf16 v[124:127], v[132:135], v[180:183], v[124:127]
	v_mfma_f32_16x16x32_bf16 v[120:123], v[140:143], v[180:183], v[120:123]
	v_mfma_f32_16x16x32_bf16 v[108:111], v[132:135], v[188:191], v[108:111]
	v_mfma_f32_16x16x32_bf16 v[104:107], v[140:143], v[188:191], v[104:107]
	v_mfma_f32_16x16x32_bf16 v[92:95], v[132:135], v[204:207], v[92:95]
	v_mfma_f32_16x16x32_bf16 v[88:91], v[140:143], v[204:207], v[88:91]
	v_mfma_f32_16x16x32_bf16 v[76:79], v[132:135], v[212:215], v[76:79]
	v_mfma_f32_16x16x32_bf16 v[72:75], v[140:143], v[212:215], v[72:75]
	s_setprio 0
	s_setprio 1
	v_mfma_f32_16x16x32_bf16 v[116:119], v[144:147], v[176:179], v[116:119]
	v_mfma_f32_16x16x32_bf16 v[112:115], v[152:155], v[176:179], v[112:115]
	v_mfma_f32_16x16x32_bf16 v[100:103], v[144:147], v[184:187], v[100:103]
	v_mfma_f32_16x16x32_bf16 v[96:99], v[152:155], v[184:187], v[96:99]
	v_mfma_f32_16x16x32_bf16 v[84:87], v[144:147], v[200:203], v[84:87]
	v_mfma_f32_16x16x32_bf16 v[80:83], v[152:155], v[200:203], v[80:83]
	v_mfma_f32_16x16x32_bf16 v[68:71], v[144:147], v[208:211], v[68:71]
	v_mfma_f32_16x16x32_bf16 v[64:67], v[152:155], v[208:211], v[64:67]
	v_mfma_f32_16x16x32_bf16 v[116:119], v[148:151], v[180:183], v[116:119]
	v_mfma_f32_16x16x32_bf16 v[112:115], v[156:159], v[180:183], v[112:115]
	v_mfma_f32_16x16x32_bf16 v[100:103], v[148:151], v[188:191], v[100:103]
	v_mfma_f32_16x16x32_bf16 v[96:99], v[156:159], v[188:191], v[96:99]
	v_mfma_f32_16x16x32_bf16 v[84:87], v[148:151], v[204:207], v[84:87]
	v_mfma_f32_16x16x32_bf16 v[80:83], v[156:159], v[204:207], v[80:83]
	v_mfma_f32_16x16x32_bf16 v[68:71], v[148:151], v[212:215], v[68:71]
	v_mfma_f32_16x16x32_bf16 v[64:67], v[156:159], v[212:215], v[64:67]
	s_setprio 0
	s_barrier
	s_add_i32 s56, s33, s81
	s_add_u32 s98, s28, s0
	s_addc_u32 s99, s29, s1
	s_mov_b32 m0, s56
	ds_read_b128 v[176:179], v197 offset:16384
	ds_read_b128 v[180:183], v197 offset:17408
	ds_read_b128 v[184:187], v197 offset:18432
	ds_read_b128 v[188:191], v197 offset:19456
	ds_read_b128 v[200:203], v197 offset:20480
	ds_read_b128 v[204:207], v197 offset:21504
	ds_read_b128 v[208:211], v197 offset:22528
	ds_read_b128 v[212:215], v197 offset:23552
	global_load_lds_dwordx4 v162, s[28:29]
	s_add_i32 m0, s56, 0x2000
	s_add_u32 s56, s28, 0x80000
	s_addc_u32 s57, s29, 0
	s_add_i32 s58, s48, s81
	global_load_lds_dwordx4 v166, s[28:29]
	s_mov_b32 m0, s58
	s_add_u32 s100, s30, s0
	s_addc_u32 s101, s31, s1
	global_load_lds_dwordx4 v162, s[56:57]
	s_add_i32 m0, s58, 0x2000
	s_nop 0
	global_load_lds_dwordx4 v166, s[56:57]
	s_mov_b32 m0, s39
	s_nop 0
	global_load_lds_dwordx4 v160, s[30:31]
	s_mov_b32 m0, s42
	s_nop 0
	global_load_lds_dwordx4 v164, s[30:31]
	s_waitcnt vmcnt(8)
	s_waitcnt lgkmcnt(0)
	s_barrier
	s_setprio 1
	s_waitcnt lgkmcnt(0)
	v_mfma_f32_16x16x32_bf16 v[60:63], v[128:131], v[176:179], v[60:63]
	v_mfma_f32_16x16x32_bf16 v[56:59], v[136:139], v[176:179], v[56:59]
	v_mfma_f32_16x16x32_bf16 v[44:47], v[128:131], v[184:187], v[44:47]
	v_mfma_f32_16x16x32_bf16 v[40:43], v[136:139], v[184:187], v[40:43]
	v_mfma_f32_16x16x32_bf16 v[28:31], v[128:131], v[200:203], v[28:31]
	v_mfma_f32_16x16x32_bf16 v[24:27], v[136:139], v[200:203], v[24:27]
	v_mfma_f32_16x16x32_bf16 v[12:15], v[128:131], v[208:211], v[12:15]
	v_mfma_f32_16x16x32_bf16 v[8:11], v[136:139], v[208:211], v[8:11]
	v_mfma_f32_16x16x32_bf16 v[60:63], v[132:135], v[180:183], v[60:63]
	v_mfma_f32_16x16x32_bf16 v[56:59], v[140:143], v[180:183], v[56:59]
	v_mfma_f32_16x16x32_bf16 v[44:47], v[132:135], v[188:191], v[44:47]
	v_mfma_f32_16x16x32_bf16 v[40:43], v[140:143], v[188:191], v[40:43]
	v_mfma_f32_16x16x32_bf16 v[28:31], v[132:135], v[204:207], v[28:31]
	v_mfma_f32_16x16x32_bf16 v[24:27], v[140:143], v[204:207], v[24:27]
	v_mfma_f32_16x16x32_bf16 v[12:15], v[132:135], v[212:215], v[12:15]
	v_mfma_f32_16x16x32_bf16 v[8:11], v[140:143], v[212:215], v[8:11]
	s_setprio 0
	s_setprio 1
	v_mfma_f32_16x16x32_bf16 v[52:55], v[144:147], v[176:179], v[52:55]
	v_mfma_f32_16x16x32_bf16 v[48:51], v[152:155], v[176:179], v[48:51]
	v_mfma_f32_16x16x32_bf16 v[36:39], v[144:147], v[184:187], v[36:39]
	v_mfma_f32_16x16x32_bf16 v[32:35], v[152:155], v[184:187], v[32:35]
	v_mfma_f32_16x16x32_bf16 v[20:23], v[144:147], v[200:203], v[20:23]
	v_mfma_f32_16x16x32_bf16 v[16:19], v[152:155], v[200:203], v[16:19]
	v_mfma_f32_16x16x32_bf16 v[4:7], v[144:147], v[208:211], v[4:7]
	v_mfma_f32_16x16x32_bf16 v[0:3], v[152:155], v[208:211], v[0:3]
	v_mfma_f32_16x16x32_bf16 v[52:55], v[148:151], v[180:183], v[52:55]
	v_mfma_f32_16x16x32_bf16 v[48:51], v[156:159], v[180:183], v[48:51]
	v_mfma_f32_16x16x32_bf16 v[36:39], v[148:151], v[188:191], v[36:39]
	v_mfma_f32_16x16x32_bf16 v[32:35], v[156:159], v[188:191], v[32:35]
	v_mfma_f32_16x16x32_bf16 v[20:23], v[148:151], v[204:207], v[20:23]
	v_mfma_f32_16x16x32_bf16 v[16:19], v[156:159], v[204:207], v[16:19]
	v_mfma_f32_16x16x32_bf16 v[4:7], v[148:151], v[212:215], v[4:7]
	v_mfma_f32_16x16x32_bf16 v[0:3], v[156:159], v[212:215], v[0:3]
	s_setprio 0
	s_barrier
; #define PG8_STAGE(bufoff, gbase, voff) do { _Pragma("unroll") for (int _i = 0; _i < 2; ++_i) \
;         __builtin_amdgcn_global_load_lds((const unsigned*)((const char*)(gbase) + (voff)[_i]), (PG8_LAS unsigned*)(lds + (bufoff) + ldsw + _i * 8192), 16, 0, 0); } while (0)
; #define PG8_LDA(dst, b, h) do { _Pragma("unroll") for (int m = 0; m < 4; ++m) _Pragma("unroll") for (int k = 0; k < 2; ++k) dst[m][k] = *(const PG8_LAS bf16x8*)(lds + PG8_SA(b, h) + aoff + m * 2048 + k * 1024); } while (0)
; #define PG8_LDB(dst, b, h) do { _Pragma("unroll") for (int n = 0; n < 2; ++n) _Pragma("unroll") for (int k = 0; k < 2; ++k) dst[n][k] = *(const PG8_LAS bf16x8*)(lds + PG8_SB(b, h) + boff + n * 2048 + k * 1024); } while (0)
; #define PG8_MMA(ai, bj, At, Bt) do { __builtin_amdgcn_s_setprio(1); _Pragma("unroll") for (int m = 0; m < 4; ++m) _Pragma("unroll") for (int n = 0; n < 2; ++n) _Pragma("unroll") for (int k = 0; k < 2; ++k) \
;         acc[ai][bj][m][n] = mma16<Epi::I8>(Bt[n][k], At[m][k], acc[ai][bj][m][n]); __builtin_amdgcn_s_setprio(0); } while (0)
; #define PG8_WAIT_V(n) asm volatile("s_waitcnt vmcnt(" #n ")" ::: "memory")
; #define PG8_WAIT_L(n) asm volatile("s_waitcnt lgkmcnt(" #n ")" ::: "memory")
; #define PG8_BAR __builtin_amdgcn_s_barrier()
; #define PG8_SCHED __builtin_amdgcn_sched_barrier(0)
; template <class Epi, class Sched, bool ALIGN_EPI = false, bool SP2 = false>
; __device__ __forceinline__ void gemm_phase(PG8_LAS unsigned char* lds, const Gemm g, const Sched& S, const Epi& E, int wid  ) {
;     ...
;             PG8_LDB(B0, 1, 0); PG8_LDB(B1, 1, 1); PG8_SCHED; PG8_LDA(At, 1, 0); PG8_STAGE(PG8_SA(0, 1), a2 + hstep, voffA);
;             PG8_WAIT_V(8); PG8_WAIT_L(0); PG8_BAR; PG8_MMA(0, 0, At, B0); PG8_MMA(0, 1, At, B1); PG8_BAR; PG8_SCHED;
;             PG8_LDA(At, 1, 1); PG8_STAGE(PG8_SB(1, 0), b3, voffB); PG8_STAGE(PG8_SB(1, 1), b3 + hstep, voffB); PG8_STAGE(PG8_SA(1, 0), a3, voffA);
;             PG8_WAIT_V(8); PG8_WAIT_L(0); PG8_BAR; PG8_MMA(1, 0, At, B0); PG8_MMA(1, 1, At, B1); PG8_BAR; PG8_SCHED;
	s_add_i32 s56, 0, 0x18000
	s_add_i32 s57, 0, 0x1c000
	v_add_u32_e32 v140, s56, v193
	v_add_u32_e32 v156, s57, v193
	ds_read_b128 v[128:131], v140
	ds_read_b128 v[132:135], v140 offset:1024
	ds_read_b128 v[136:139], v140 offset:2048
	ds_read_b128 v[140:143], v140 offset:3072
	ds_read_b128 v[144:147], v156
	ds_read_b128 v[148:151], v156 offset:1024
	ds_read_b128 v[152:155], v156 offset:2048
	ds_read_b128 v[156:159], v156 offset:3072
	s_add_u32 s30, s30, 0x80000
	s_addc_u32 s31, s31, 0
	s_mov_b32 m0, s43
	ds_read_b128 v[176:179], v197 offset:32768
	ds_read_b128 v[180:183], v197 offset:33792
	ds_read_b128 v[184:187], v197 offset:34816
	ds_read_b128 v[188:191], v197 offset:35840
	ds_read_b128 v[200:203], v197 offset:36864
	ds_read_b128 v[204:207], v197 offset:37888
	ds_read_b128 v[208:211], v197 offset:38912
	ds_read_b128 v[212:215], v197 offset:39936
	global_load_lds_dwordx4 v160, s[30:31]
	s_mov_b32 m0, s44
	s_nop 0
	global_load_lds_dwordx4 v164, s[30:31]
	s_waitcnt vmcnt(8)
	s_waitcnt lgkmcnt(0)
	s_barrier
	s_setprio 1
	s_waitcnt lgkmcnt(0)
	v_mfma_f32_16x16x32_bf16 v[124:127], v[128:131], v[176:179], v[124:127]
	v_mfma_f32_16x16x32_bf16 v[120:123], v[136:139], v[176:179], v[120:123]
	v_mfma_f32_16x16x32_bf16 v[108:111], v[128:131], v[184:187], v[108:111]
	v_mfma_f32_16x16x32_bf16 v[104:107], v[136:139], v[184:187], v[104:107]
	v_mfma_f32_16x16x32_bf16 v[92:95], v[128:131], v[200:203], v[92:95]
	v_mfma_f32_16x16x32_bf16 v[88:91], v[136:139], v[200:203], v[88:91]
	v_mfma_f32_16x16x32_bf16 v[76:79], v[128:131], v[208:211], v[76:79]
	v_mfma_f32_16x16x32_bf16 v[72:75], v[136:139], v[208:211], v[72:75]
	v_mfma_f32_16x16x32_bf16 v[124:127], v[132:135], v[180:183], v[124:127]
	v_mfma_f32_16x16x32_bf16 v[120:123], v[140:143], v[180:183], v[120:123]
	v_mfma_f32_16x16x32_bf16 v[108:111], v[132:135], v[188:191], v[108:111]
	v_mfma_f32_16x16x32_bf16 v[104:107], v[140:143], v[188:191], v[104:107]
	v_mfma_f32_16x16x32_bf16 v[92:95], v[132:135], v[204:207], v[92:95]
	v_mfma_f32_16x16x32_bf16 v[88:91], v[140:143], v[204:207], v[88:91]
	v_mfma_f32_16x16x32_bf16 v[76:79], v[132:135], v[212:215], v[76:79]
	v_mfma_f32_16x16x32_bf16 v[72:75], v[140:143], v[212:215], v[72:75]
	s_setprio 0
	s_setprio 1
	v_mfma_f32_16x16x32_bf16 v[116:119], v[144:147], v[176:179], v[116:119]
	v_mfma_f32_16x16x32_bf16 v[112:115], v[152:155], v[176:179], v[112:115]
	v_mfma_f32_16x16x32_bf16 v[100:103], v[144:147], v[184:187], v[100:103]
	v_mfma_f32_16x16x32_bf16 v[96:99], v[152:155], v[184:187], v[96:99]
	v_mfma_f32_16x16x32_bf16 v[84:87], v[144:147], v[200:203], v[84:87]
	v_mfma_f32_16x16x32_bf16 v[80:83], v[152:155], v[200:203], v[80:83]
	v_mfma_f32_16x16x32_bf16 v[68:71], v[144:147], v[208:211], v[68:71]
	v_mfma_f32_16x16x32_bf16 v[64:67], v[152:155], v[208:211], v[64:67]
	v_mfma_f32_16x16x32_bf16 v[116:119], v[148:151], v[180:183], v[116:119]
	v_mfma_f32_16x16x32_bf16 v[112:115], v[156:159], v[180:183], v[112:115]
	v_mfma_f32_16x16x32_bf16 v[100:103], v[148:151], v[188:191], v[100:103]
	v_mfma_f32_16x16x32_bf16 v[96:99], v[156:159], v[188:191], v[96:99]
	v_mfma_f32_16x16x32_bf16 v[84:87], v[148:151], v[204:207], v[84:87]
	v_mfma_f32_16x16x32_bf16 v[80:83], v[156:159], v[204:207], v[80:83]
	v_mfma_f32_16x16x32_bf16 v[68:71], v[148:151], v[212:215], v[68:71]
	v_mfma_f32_16x16x32_bf16 v[64:67], v[156:159], v[212:215], v[64:67]
	s_setprio 0
	s_barrier
	s_add_i32 s30, s56, s81
	s_mov_b32 m0, s30
	ds_read_b128 v[176:179], v197 offset:49152
	ds_read_b128 v[180:183], v197 offset:50176
	ds_read_b128 v[184:187], v197 offset:51200
	ds_read_b128 v[188:191], v197 offset:52224
	ds_read_b128 v[200:203], v197 offset:53248
	ds_read_b128 v[204:207], v197 offset:54272
	ds_read_b128 v[208:211], v197 offset:55296
	ds_read_b128 v[212:215], v197 offset:56320
	global_load_lds_dwordx4 v162, s[98:99]
	s_add_i32 m0, s30, 0x2000
	s_add_u32 s28, s28, 0x80080
	s_addc_u32 s29, s29, 0
	s_add_i32 s30, s57, s81
	global_load_lds_dwordx4 v166, s[98:99]
	s_mov_b32 m0, s30
	s_nop 0
	global_load_lds_dwordx4 v162, s[28:29]
	s_add_i32 m0, s30, 0x2000
	s_nop 0
	global_load_lds_dwordx4 v166, s[28:29]
	s_mov_b32 m0, s46
	s_nop 0
	global_load_lds_dwordx4 v160, s[100:101]
	s_mov_b32 m0, s47
	s_nop 0
	global_load_lds_dwordx4 v164, s[100:101]
	s_waitcnt vmcnt(8)
	s_waitcnt lgkmcnt(0)
	s_barrier
	s_setprio 1
	s_waitcnt lgkmcnt(0)
	v_mfma_f32_16x16x32_bf16 v[60:63], v[128:131], v[176:179], v[60:63]
	v_mfma_f32_16x16x32_bf16 v[56:59], v[136:139], v[176:179], v[56:59]
	v_mfma_f32_16x16x32_bf16 v[44:47], v[128:131], v[184:187], v[44:47]
	v_mfma_f32_16x16x32_bf16 v[40:43], v[136:139], v[184:187], v[40:43]
	v_mfma_f32_16x16x32_bf16 v[28:31], v[128:131], v[200:203], v[28:31]
	v_mfma_f32_16x16x32_bf16 v[24:27], v[136:139], v[200:203], v[24:27]
	v_mfma_f32_16x16x32_bf16 v[12:15], v[128:131], v[208:211], v[12:15]
	v_mfma_f32_16x16x32_bf16 v[8:11], v[136:139], v[208:211], v[8:11]
	v_mfma_f32_16x16x32_bf16 v[60:63], v[132:135], v[180:183], v[60:63]
	v_mfma_f32_16x16x32_bf16 v[56:59], v[140:143], v[180:183], v[56:59]
	v_mfma_f32_16x16x32_bf16 v[44:47], v[132:135], v[188:191], v[44:47]
	v_mfma_f32_16x16x32_bf16 v[40:43], v[140:143], v[188:191], v[40:43]
	v_mfma_f32_16x16x32_bf16 v[28:31], v[132:135], v[204:207], v[28:31]
	v_mfma_f32_16x16x32_bf16 v[24:27], v[140:143], v[204:207], v[24:27]
	v_mfma_f32_16x16x32_bf16 v[12:15], v[132:135], v[212:215], v[12:15]
	v_mfma_f32_16x16x32_bf16 v[8:11], v[140:143], v[212:215], v[8:11]
	s_setprio 0
	s_setprio 1
	v_mfma_f32_16x16x32_bf16 v[52:55], v[144:147], v[176:179], v[52:55]
	v_mfma_f32_16x16x32_bf16 v[48:51], v[152:155], v[176:179], v[48:51]
	v_mfma_f32_16x16x32_bf16 v[36:39], v[144:147], v[184:187], v[36:39]
	v_mfma_f32_16x16x32_bf16 v[32:35], v[152:155], v[184:187], v[32:35]
	v_mfma_f32_16x16x32_bf16 v[20:23], v[144:147], v[200:203], v[20:23]
	v_mfma_f32_16x16x32_bf16 v[16:19], v[152:155], v[200:203], v[16:19]
	v_mfma_f32_16x16x32_bf16 v[4:7], v[144:147], v[208:211], v[4:7]
	v_mfma_f32_16x16x32_bf16 v[0:3], v[152:155], v[208:211], v[0:3]
	v_mfma_f32_16x16x32_bf16 v[52:55], v[148:151], v[180:183], v[52:55]
	v_mfma_f32_16x16x32_bf16 v[48:51], v[156:159], v[180:183], v[48:51]
	v_mfma_f32_16x16x32_bf16 v[36:39], v[148:151], v[188:191], v[36:39]
	v_mfma_f32_16x16x32_bf16 v[32:35], v[156:159], v[188:191], v[32:35]
	v_mfma_f32_16x16x32_bf16 v[20:23], v[148:151], v[204:207], v[20:23]
	v_mfma_f32_16x16x32_bf16 v[16:19], v[156:159], v[204:207], v[16:19]
	v_mfma_f32_16x16x32_bf16 v[4:7], v[148:151], v[212:215], v[4:7]
	v_mfma_f32_16x16x32_bf16 v[0:3], v[156:159], v[212:215], v[0:3]
	s_setprio 0
	s_barrier
	s_add_i32 s55, s55, 2
	s_add_u32 s26, s26, 0x100
	s_addc_u32 s27, s27, 0
	s_add_u32 s53, s53, 0x100
	s_addc_u32 s54, s54, 0
	s_cmp_gt_u32 s55, 29
	s_cbranch_scc0 .LBB0_510
	s_and_b64 vcc, exec, s[78:79]
	s_cbranch_vccz .LBB0_513
	s_barrier
